# attention QK^T: 12 K-fragment LDS reads issued up front into fresh registers, MFMAs with counted lgkmcnt waits (on v46)
# speedup vs baseline: 1.0095x; 1.0037x over previous
; #define LAS __attribute__((address_space(3)))
; __device__ __forceinline__ int crow(int r, int hi) { return (r & 3) + 8 * (r >> 2) + 4 * hi; }
; __device__ __forceinline__ void attn_bh(const Ctx& F, int b, int h) {
;     ...
;             if (kv0 <= wlast) {
;                 f32x16 p0, p1;
; #pragma unroll
;                 for (int r = 0; r < 16; ++r) { p0[r] = 0.f; p1[r] = 0.f; }
; #pragma unroll
;                 for (int d0 = 0; d0 < 6; ++d0) {
;                     const bf16x8 a0 = *(const LAS bf16x8*)(Kl + q31 * KP + (16 * d0 + 8 * hi) * 2);
;                     const bf16x8 a1 = *(const LAS bf16x8*)(Kl + (32 + q31) * KP + (16 * d0 + 8 * hi) * 2);
;                     p0 = __builtin_amdgcn_mfma_f32_32x32x16_bf16(a0, qf[d0], p0, 0, 0, 0);
;                     p1 = __builtin_amdgcn_mfma_f32_32x32x16_bf16(a1, qf[d0], p1, 0, 0, 0);
;                 }
;                 if (kv0 + 63 > q0 + 32 * w) {
; #pragma unroll
;                     for (int r = 0; r < 16; ++r) { const int kv = kv0 + crow(r, hi); if (kv > qrow) p0[r] = -INFINITY; if (kv + 32 > qrow) p1[r] = -INFINITY; }
;                 }
.LBB0_782:
	s_sub_i32 s22, s43, 63
	s_cmp_gt_u32 s22, s42
	s_cbranch_scc1 .LBB0_775
	ds_read_b128 v[180:183], v174
	ds_read_b128 v[184:187], v174 offset:6656
	ds_read_b128 v[188:191], v174 offset:32
	ds_read_b128 v[192:195], v174 offset:6688
	ds_read_b128 v[196:199], v174 offset:64
	ds_read_b128 v[200:203], v174 offset:6720
	ds_read_b128 v[204:207], v174 offset:96
	ds_read_b128 v[208:211], v174 offset:6752
	ds_read_b128 v[212:215], v174 offset:128
	ds_read_b128 v[216:219], v174 offset:6784
	ds_read_b128 v[220:223], v174 offset:160
	ds_read_b128 v[224:227], v174 offset:6816
	s_cmp_le_u32 s43, s39
	s_waitcnt lgkmcnt(11)
	v_mfma_f32_32x32x16_bf16 v[50:65], v[180:183], v[86:89], 0
	s_waitcnt lgkmcnt(10)
	v_mfma_f32_32x32x16_bf16 v[34:49], v[184:187], v[86:89], 0
	s_waitcnt lgkmcnt(9)
	v_mfma_f32_32x32x16_bf16 v[50:65], v[188:191], v[66:69], v[50:65]
	s_waitcnt lgkmcnt(8)
	v_mfma_f32_32x32x16_bf16 v[34:49], v[192:195], v[66:69], v[34:49]
	s_waitcnt lgkmcnt(7)
	v_mfma_f32_32x32x16_bf16 v[50:65], v[196:199], v[70:73], v[50:65]
	s_waitcnt lgkmcnt(6)
	v_mfma_f32_32x32x16_bf16 v[34:49], v[200:203], v[70:73], v[34:49]
	s_waitcnt lgkmcnt(5)
	v_mfma_f32_32x32x16_bf16 v[50:65], v[204:207], v[74:77], v[50:65]
	s_waitcnt lgkmcnt(4)
	v_mfma_f32_32x32x16_bf16 v[34:49], v[208:211], v[74:77], v[34:49]
	s_waitcnt lgkmcnt(3)
	v_mfma_f32_32x32x16_bf16 v[50:65], v[212:215], v[78:81], v[50:65]
	s_waitcnt lgkmcnt(2)
	v_mfma_f32_32x32x16_bf16 v[34:49], v[216:219], v[78:81], v[34:49]
	s_waitcnt lgkmcnt(1)
	v_mfma_f32_32x32x16_bf16 v[50:65], v[220:223], v[82:85], v[50:65]
	s_waitcnt lgkmcnt(0)
	v_mfma_f32_32x32x16_bf16 v[34:49], v[224:227], v[82:85], v[34:49]
	s_cbranch_scc1 .LBB0_785
	v_add_u32_e32 v1, s43, v112
	v_subrev_u32_e32 v159, 63, v1
	v_cmp_le_i32_e32 vcc, v159, v129
	v_subrev_u32_e32 v160, 61, v1
	v_subrev_u32_e32 v1, 60, v1
	s_nop 5
	v_cndmask_b32_e32 v34, v121, v34, vcc
	v_cmp_lt_i32_e32 vcc, v159, v128
	s_nop 1
	v_cndmask_b32_e32 v51, v121, v51, vcc
	v_cmp_le_i32_e32 vcc, v159, v128
	s_nop 1
	v_cndmask_b32_e32 v50, v121, v50, vcc
	v_cmp_le_i32_e32 vcc, v159, v130
	s_nop 1
	v_cndmask_b32_e32 v35, v121, v35, vcc
	v_cmp_le_i32_e32 vcc, v160, v128
	s_nop 1
	v_cndmask_b32_e32 v52, v121, v52, vcc
	v_cmp_le_i32_e32 vcc, v159, v131
	s_nop 1
	v_cndmask_b32_e32 v36, v121, v36, vcc
	v_cmp_le_i32_e32 vcc, v1, v128
	s_nop 1
	v_cndmask_b32_e32 v53, v121, v53, vcc
	v_cmp_le_i32_e32 vcc, v159, v132
	s_nop 1
	v_cndmask_b32_e32 v37, v121, v37, vcc
	v_cmp_le_i32_e32 vcc, v159, v133
	s_nop 1
	v_cndmask_b32_e32 v54, v121, v54, vcc
	v_cmp_le_i32_e32 vcc, v159, v134
	s_nop 1
	v_cndmask_b32_e32 v38, v121, v38, vcc
	v_cmp_le_i32_e32 vcc, v159, v135
	s_nop 1
	v_cndmask_b32_e32 v55, v121, v55, vcc
	v_cmp_le_i32_e32 vcc, v159, v136
	s_nop 1
	v_cndmask_b32_e32 v39, v121, v39, vcc
	v_cmp_le_i32_e32 vcc, v159, v137
	s_nop 1
	v_cndmask_b32_e32 v56, v121, v56, vcc
	v_cmp_le_i32_e32 vcc, v159, v138
	s_nop 1
	v_cndmask_b32_e32 v40, v121, v40, vcc
	v_cmp_le_i32_e32 vcc, v159, v139
	s_nop 1
	v_cndmask_b32_e32 v57, v121, v57, vcc
	v_cmp_le_i32_e32 vcc, v159, v140
	s_nop 1
	v_cndmask_b32_e32 v41, v121, v41, vcc
	v_cmp_le_i32_e32 vcc, v159, v141
	s_nop 1
	v_cndmask_b32_e32 v58, v121, v58, vcc
	v_cmp_le_i32_e32 vcc, v159, v142
	s_nop 1
	v_cndmask_b32_e32 v42, v121, v42, vcc
	v_cmp_le_i32_e32 vcc, v159, v143
	s_nop 1
	v_cndmask_b32_e32 v59, v121, v59, vcc
	v_cmp_le_i32_e32 vcc, v159, v144
	s_nop 1
	v_cndmask_b32_e32 v43, v121, v43, vcc
	v_cmp_le_i32_e32 vcc, v159, v145
	s_nop 1
	v_cndmask_b32_e32 v60, v121, v60, vcc
	v_cmp_le_i32_e32 vcc, v159, v146
	s_nop 1
	v_cndmask_b32_e32 v44, v121, v44, vcc
	v_cmp_le_i32_e32 vcc, v159, v147
	s_nop 1
	v_cndmask_b32_e32 v61, v121, v61, vcc
	v_cmp_le_i32_e32 vcc, v159, v148
	s_nop 1
	v_cndmask_b32_e32 v45, v121, v45, vcc
	v_cmp_le_i32_e32 vcc, v159, v149
	s_nop 1
	v_cndmask_b32_e32 v62, v121, v62, vcc
	v_cmp_le_i32_e32 vcc, v159, v150
	s_nop 1
	v_cndmask_b32_e32 v46, v121, v46, vcc
	v_cmp_le_i32_e32 vcc, v159, v151
	s_nop 1
	v_cndmask_b32_e32 v63, v121, v63, vcc
	v_cmp_le_i32_e32 vcc, v159, v152
	s_nop 1
	v_cndmask_b32_e32 v47, v121, v47, vcc
	v_cmp_le_i32_e32 vcc, v159, v153
	s_nop 1
	v_cndmask_b32_e32 v64, v121, v64, vcc
	v_cmp_le_i32_e32 vcc, v159, v154
	s_nop 1
	v_cndmask_b32_e32 v48, v121, v48, vcc
	v_cmp_le_i32_e32 vcc, v159, v155
	s_nop 1
	v_cndmask_b32_e32 v65, v121, v65, vcc
	v_cmp_le_i32_e32 vcc, v159, v157
	s_nop 1
	v_cndmask_b32_e32 v49, v121, v49, vcc
